# stagger: workgroups with blockIdx bit 3 set sleep ~770 clocks once at FFN up/down GEMM phase entry to offset the two co-resident blocks by half a stage
# speedup vs baseline: 1.0034x; 1.0034x over previous
; DI GemmDesc make_desc(const Params& p, int gi) {
;     ...
;   } else if (gi < 12) {
;     const int l = (gi - 4) >> 1;
;     if (((gi - 4) & 1) == 0) {
;       d.Bt = p.w_gu + (size_t)l * 5632 * 1024; d.N = 5632; d.epi = EPI_SWIGLU; d.ssq_in = ssq + (size_t)(2 * l) * M; d.act = p.R;
;     } else {
;       d.A = p.R; d.lda = DFF; d.K = DFF; d.Bt = p.w_dn + (size_t)l * 1024 * DFF; d.ldb = DFF; d.ssq_out = ssq + (size_t)(2 * l + 1) * M;
;     }
; DI void run_ffn(const Params& p, int l, bool down, bf16_t* smem) { const GemmDesc d = make_desc(p, 4 + 2 * l + (down ? 1 : 0)); if (PROBE_ON && p.probe & 2) gemm_phase(d, smem, p.dryv); if ((PROBE_ON && p.probe & 64) && !down) gemm_phase(d, smem, 0); if ((PROBE_ON && p.probe & 512) && !down) gemm_ph ...
.LBB0_1455:
	s_andn2_b64 vcc, exec, s[4:5]
	s_cbranch_vccnz .LBB0_1521
	v_readlane_b32 s4, v228, 41
	v_readlane_b32 s5, v228, 42
	s_andn2_b64 vcc, exec, s[4:5]
	s_cbranch_vccnz .LBB0_1471
	v_readlane_b32 s4, v228, 51
	v_readlane_b32 s8, v228, 56
	s_mul_i32 s1, s4, 0xb00000
	v_readlane_b32 s10, v228, 58
	v_readlane_b32 s11, v228, 59
	s_add_u32 s6, s10, s1
	s_addc_u32 s7, s11, 0
	s_mul_i32 s1, s4, 0x80400
	v_readlane_b32 s9, v228, 57
	s_add_u32 s8, s58, s1
	s_addc_u32 s9, s59, 0
	v_readlane_b32 s1, v228, 39
	v_readlane_b32 s100, v229, 2
	s_and_b32 s100, s100, 0x8
	s_cmp_lg_u32 s100, 0
	s_cbranch_scc0 .Lstag_up
	s_sleep 12
.Lstag_up:
	s_branch .LBB0_1459
.LBB0_1458:
	s_add_i32 s1, s1, s39
	v_readlane_b32 s4, v228, 40
	s_cmp_lt_u32 s1, s4
	s_barrier
	s_cbranch_scc0 .LBB0_1471

; DI GemmDesc make_desc(const Params& p, int gi) {
;     ...
;   } else if (gi < 12) {
;     const int l = (gi - 4) >> 1;
;     if (((gi - 4) & 1) == 0) {
;       d.Bt = p.w_gu + (size_t)l * 5632 * 1024; d.N = 5632; d.epi = EPI_SWIGLU; d.ssq_in = ssq + (size_t)(2 * l) * M; d.act = p.R;
;     } else {
;       d.A = p.R; d.lda = DFF; d.K = DFF; d.Bt = p.w_dn + (size_t)l * 1024 * DFF; d.ldb = DFF; d.ssq_out = ssq + (size_t)(2 * l + 1) * M;
;     }
; DI void run_ffn(const Params& p, int l, bool down, bf16_t* smem) { const GemmDesc d = make_desc(p, 4 + 2 * l + (down ? 1 : 0)); if (PROBE_ON && p.probe & 2) gemm_phase(d, smem, p.dryv); if ((PROBE_ON && p.probe & 64) && !down) gemm_phase(d, smem, 0); if ((PROBE_ON && p.probe & 512) && !down) gemm_ph ...
.LBB0_1523:
	s_andn2_b64 vcc, exec, s[4:5]
	s_cbranch_vccnz .Ltramp_171
	v_readlane_b32 s4, v228, 14
	v_readlane_b32 s5, v228, 15
	s_andn2_b64 vcc, exec, s[4:5]
	s_cbranch_vccnz .LBB0_1593
	v_readlane_b32 s4, v228, 51
	s_mul_i32 s1, s4, 0x580000
	v_readlane_b32 s6, v228, 54
	v_readlane_b32 s7, v228, 55
	s_add_u32 s6, s6, s1
	s_addc_u32 s7, s7, 0
	s_mul_i32 s1, s4, 0x80400
	s_add_u32 s1, s58, s1
	s_addc_u32 s4, s59, 0
	s_add_u32 s8, s1, 0x40200
	s_addc_u32 s9, s4, 0
	v_readlane_b32 s12, v228, 39
	v_readlane_b32 s100, v229, 2
	s_and_b32 s100, s100, 0x8
	s_cmp_lg_u32 s100, 0
	s_cbranch_scc0 .Lstag_dn
	s_sleep 12
.Lstag_dn:
	s_branch .LBB0_1527
.LBB0_1526:
	s_or_b64 exec, exec, s[4:5]
	s_add_i32 s12, s12, s39
	v_readlane_b32 s1, v228, 13
	s_cmp_lt_u32 s12, s1
	s_waitcnt lgkmcnt(0)
	s_barrier
	s_cbranch_scc0 .LBB0_1593
